# dense attention: ping-pong halves (2 barriers per tile, waves 4-7 one barrier behind), V ring 3-deep, DMA issued off the QK-softmax chain with counted vmcnt
# speedup vs baseline: 1.0167x; 1.0167x over previous
; __device__ __forceinline__ int v_rd_base(int lane) { return ((lane & 3) << 3) | (((lane >> 2) & 3) << 6) | (((lane >> 4) & 1) << 5) | (((lane >> 5) & 1) << 8); }
; #define LAS3 __attribute__((address_space(3)))
; template <int LDO>
; __device__ __forceinline__ void attn_unit_dv(const bf16_t* __restrict__ Qb, const bf16_t* __restrict__ Kh, const bf16_t* __restrict__ Vh, bf16_t* __restrict__ Ob, int NT, char* lds, LAS3 unsigned char* ldsl) {
;   const int tid = threadIdx.x, lane = tid & 63, r32 = lane & 31, hi = lane >> 5; const int wid = __builtin_amdgcn_readfirstlane(tid >> 6);
;   float* ws = (float*)(lds + DV_WS) + wid * 64; float* li_l = ws; float* al_l = ws + 32;
;   float m_reg = -1e30f, l_reg = 0.f; f32x16 o[8] = {}; bf16x8 qr[8];
;   const unsigned koff0 = (unsigned)((8 * wid + (lane >> 4)) * (LDK * 2) + (((lane & 15) ^ (lane >> 4)) << 4));
;   const int hf = wid >> 2;
;   unsigned voff0;
;   { const int lc = (4 * wid) & 15, b = lc * 1024 + 16 * lane, sub = b >> 9, e = (b & 511) >> 1;
;     const int kk = (sub >> 2) * 8 + (e >> 5), c = (sub & 3) * 32 + (e & 31), k = (kk & ~0xC) | ((kk & 4) << 1) | ((kk & 8) >> 1);
;     voff0 = (unsigned)(k * (LDV2 * 2) + (hf * 128 + c) * 2); }
;   LAS3 unsigned char* kdst = ldsl + DV_K0 + wid * 2048;
;   LAS3 unsigned char* vdst = ldsl + DV_V0 + hf * 16384 + ((4 * wid) & 15) * 1024;
;     ...
;   if (wid >= 4) __builtin_amdgcn_s_setprio(1);
;   DMA_KV(0, 0);
;   const bf16_t* Qw = Qb + (long)(wid * QBLK + r32) * LDQ + hi * 8;
; #pragma unroll
;   for (int d0 = 0; d0 < 8; ++d0) qr[d0] = ld8(Qw + d0 * 16);
;   const int vb0 = (int)(uintptr_t)(lds + DV_V0) + v_rd_base(lane);
;   asm volatile("s_waitcnt vmcnt(0) lgkmcnt(0)" ::: "memory"); __builtin_amdgcn_s_barrier(); asm volatile("" ::: "memory");
.LBB0_640:
	v_readfirstlane_b32 s0, v194
	s_cmpk_lt_u32 s0, 0x100
	s_cbranch_scc1 .LBB0_642
	s_setprio 0
.LBB0_642:
	v_readfirstlane_b32 s99, v194
	s_bfe_u32 s31, s28, 0x10009
	s_bfe_u32 s30, s28, 0x20007
	s_lshl_b32 s1, s31, 3
	s_lshl_b32 s4, s30, 1
	s_bfe_u32 s29, s28, 0x10006
	s_or_b32 s1, s1, s4
	s_or_b32 s1, s1, s29
	s_lshl_b32 s33, s1, 22
	s_lshl_b32 s1, s28, 8
	s_and_b32 s34, s1, 0x3f00
	s_lshl_b32 s1, s34, 8
	s_or_b32 s1, s1, s33
	s_add_u32 s68, s42, s1
	s_addc_u32 s69, s43, 0
	s_add_u32 s78, s44, s33
	s_addc_u32 s79, s45, 0
	s_lshl_b32 s1, s30, 23
	s_lshl_b32 s4, s31, 25
	s_or_b32 s80, s4, s1
	s_add_u32 s82, s48, s80
	s_addc_u32 s83, s49, 0
	s_lshr_b32 s1, s0, 6
	s_lshr_b32 s35, s0, 2
	s_lshl_b32 s4, s1, 11
	s_and_b32 s98, s1, 1
	s_lshl_b32 s98, s98, 7
	s_or_b32 s98, s98, s4
	s_and_b32 s35, s35, 48
	s_and_b32 s84, s0, 0xffffff00
	s_lshl_b32 s66, s0, 6
	v_or_b32_e32 v3, s35, v226
	v_or_b32_e32 v0, s84, v222
	s_add_i32 s35, s4, 0
	v_xor_b32_e32 v2, s98, v221
	s_and_b32 s67, s66, 0x3000
	v_lshl_add_u32 v4, v3, 9, v0
	s_and_b32 s66, s66, 0x7fffc000
	s_mov_b32 m0, s35
	v_xor_b32_e32 v0, 64, v2
	s_add_i32 s66, s66, 0
	global_load_lds_dwordx4 v2, s[78:79]
	v_lshl_add_u64 v[6:7], s[78:79], 0, v[0:1]
	s_mov_b64 s[78:79], 0x400
	s_add_i32 s66, s66, s67
	v_lshl_add_u64 v[6:7], v[6:7], 0, s[78:79]
	s_add_i32 m0, s35, 0x400
	v_mov_b32_e32 v5, v1
	global_load_lds_dwordx4 v[6:7], off
	v_lshl_add_u64 v[6:7], s[82:83], 0, v[4:5]
	s_add_i32 m0, s66, 0x8000
	s_mov_b64 s[78:79], 0x80
	global_load_lds_dwordx4 v4, s[82:83]
	v_lshl_add_u64 v[4:5], v[6:7], 0, s[78:79]
	s_add_i32 m0, s66, 0x8400
	s_mov_b64 s[78:79], 0x800
	global_load_lds_dwordx4 v[4:5], off
	v_lshl_add_u64 v[4:5], v[6:7], 0, s[78:79]
	s_add_i32 m0, s66, 0x8800
	s_mov_b64 s[78:79], 0x880
	global_load_lds_dwordx4 v[4:5], off
	v_lshl_add_u64 v[4:5], v[6:7], 0, s[78:79]
	s_add_i32 m0, s66, 0x8c00
	s_lshl_b32 s4, s1, 5
	global_load_lds_dwordx4 v[4:5], off
	v_or_b32_e32 v4, s4, v198
	v_mov_b32_e32 v5, v1
	v_lshlrev_b64 v[4:5], 8, v[4:5]
	v_lshl_add_u64 v[4:5], s[68:69], 0, v[4:5]
	v_lshl_add_u64 v[4:5], v[4:5], 0, v[196:197]
	global_load_dwordx4 v[162:165], v[4:5], off
	global_load_dwordx4 v[166:169], v[4:5], off offset:32
	global_load_dwordx4 v[170:173], v[4:5], off offset:64
	global_load_dwordx4 v[174:177], v[4:5], off offset:96
	global_load_dwordx4 v[178:181], v[4:5], off offset:128
	global_load_dwordx4 v[182:185], v[4:5], off offset:160
	global_load_dwordx4 v[186:189], v[4:5], off offset:192
	global_load_dwordx4 v[190:193], v[4:5], off offset:224
	s_and_b32 s0, s0, 0x3fffffc0
	s_lshl_b32 s0, s0, 2
	s_add_i32 s67, s0, 0
	s_add_i32 s67, s67, 0x20000
	s_add_u32 s0, s33, 0x2fe04400
	s_addc_u32 s1, 0, 0
	v_lshl_or_b32 v3, v3, 9, v227
	v_lshl_add_u64 v[204:205], s[0:1], 0, v[0:1]
	s_add_u32 s0, s33, 0x2fe04000
	s_mov_b32 s81, s5
	v_add_u32_e32 v4, s84, v3
	v_mov_b32_e32 v5, v1
	s_addc_u32 s1, 0, 0
	v_mov_b32_e32 v3, v1
	s_waitcnt vmcnt(0)
	v_mov_b32_e32 v14, v1
	v_mov_b32_e32 v15, v1
	s_waitcnt vmcnt(0) lgkmcnt(0)
	s_barrier
	v_lshl_add_u64 v[202:203], s[80:81], 0, v[4:5]
	v_lshl_add_u64 v[206:207], s[0:1], 0, v[2:3]
	v_mov_b32_e32 v0, v1
	v_mov_b32_e32 v2, v1
	v_mov_b32_e32 v4, v1
	v_mov_b32_e32 v6, v1
	v_mov_b32_e32 v7, v1
	v_mov_b32_e32 v8, v1
	v_mov_b32_e32 v9, v1
	v_mov_b32_e32 v10, v1
	v_mov_b32_e32 v11, v1
	v_mov_b32_e32 v12, v1
	v_mov_b32_e32 v13, v1
	v_mov_b64_e32 v[128:129], v[14:15]
	v_mov_b64_e32 v[112:113], v[14:15]
	v_mov_b64_e32 v[96:97], v[14:15]
	v_mov_b64_e32 v[80:81], v[14:15]
	v_mov_b64_e32 v[64:65], v[14:15]
	v_mov_b64_e32 v[48:49], v[14:15]
	v_mov_b64_e32 v[32:33], v[14:15]
	v_mov_b64_e32 v[126:127], v[12:13]
	v_mov_b64_e32 v[124:125], v[10:11]
	v_mov_b64_e32 v[122:123], v[8:9]
	v_mov_b64_e32 v[120:121], v[6:7]
	v_mov_b64_e32 v[118:119], v[4:5]
	v_mov_b64_e32 v[116:117], v[2:3]
	v_mov_b64_e32 v[114:115], v[0:1]
	v_mov_b64_e32 v[110:111], v[12:13]
	v_mov_b64_e32 v[108:109], v[10:11]
	v_mov_b64_e32 v[106:107], v[8:9]
	v_mov_b64_e32 v[104:105], v[6:7]
	v_mov_b64_e32 v[102:103], v[4:5]
	v_mov_b64_e32 v[100:101], v[2:3]
	v_mov_b64_e32 v[98:99], v[0:1]
	v_mov_b64_e32 v[94:95], v[12:13]
	v_mov_b64_e32 v[92:93], v[10:11]
	v_mov_b64_e32 v[90:91], v[8:9]
	v_mov_b64_e32 v[88:89], v[6:7]
	v_mov_b64_e32 v[86:87], v[4:5]
	v_mov_b64_e32 v[84:85], v[2:3]
	v_mov_b64_e32 v[82:83], v[0:1]
	v_mov_b64_e32 v[78:79], v[12:13]
	v_mov_b64_e32 v[76:77], v[10:11]
	v_mov_b64_e32 v[74:75], v[8:9]
	v_mov_b64_e32 v[72:73], v[6:7]
	v_mov_b64_e32 v[70:71], v[4:5]
	v_mov_b64_e32 v[68:69], v[2:3]
	v_mov_b64_e32 v[66:67], v[0:1]
	v_mov_b64_e32 v[62:63], v[12:13]
	v_mov_b64_e32 v[60:61], v[10:11]
	v_mov_b64_e32 v[58:59], v[8:9]
	v_mov_b64_e32 v[56:57], v[6:7]
	v_mov_b64_e32 v[54:55], v[4:5]
	v_mov_b64_e32 v[52:53], v[2:3]
	v_mov_b64_e32 v[50:51], v[0:1]
	v_mov_b64_e32 v[46:47], v[12:13]
	v_mov_b64_e32 v[44:45], v[10:11]
	v_mov_b64_e32 v[42:43], v[8:9]
	v_mov_b64_e32 v[40:41], v[6:7]
	v_mov_b64_e32 v[38:39], v[4:5]
	v_mov_b64_e32 v[36:37], v[2:3]
	v_mov_b64_e32 v[34:35], v[0:1]
	v_mov_b64_e32 v[30:31], v[12:13]
	v_mov_b64_e32 v[28:29], v[10:11]
	v_mov_b64_e32 v[26:27], v[8:9]
	v_mov_b64_e32 v[24:25], v[6:7]
	v_mov_b64_e32 v[22:23], v[4:5]
	v_mov_b64_e32 v[20:21], v[2:3]
	v_mov_b64_e32 v[18:19], v[0:1]
	v_mov_b64_e32 v[16:17], v[14:15]
	v_readlane_b32 s70, v244, 42
	v_lshl_add_u32 v228, v198, 2, s67
	s_mov_b32 s68, 0
	v_mov_b32_e32 v230, 0
	v_mov_b32_e32 v229, 0xf149f2ca
	v_mov_b64_e32 v[14:15], v[12:13]
	v_mov_b64_e32 v[12:13], v[10:11]
	v_mov_b64_e32 v[10:11], v[8:9]
	v_mov_b64_e32 v[8:9], v[6:7]
	v_mov_b64_e32 v[6:7], v[4:5]
	v_mov_b64_e32 v[4:5], v[2:3]
	v_mov_b64_e32 v[2:3], v[0:1]
	v_readlane_b32 s71, v244, 43
	s_mov_b32 s98, 0
	s_mov_b32 s100, 1
	s_mov_b32 s101, 2
	s_cmpk_lt_u32 s99, 0x100
	s_cbranch_scc1 .Lpl_pre_e
	s_add_i32 s0, s35, 0x4000
	v_lshl_add_u64 v[254:255], s[22:23], 0, v[206:207]
	s_mov_b32 m0, s0
	s_nop 0
	global_load_lds_dwordx4 v[254:255], off
	v_lshl_add_u64 v[254:255], s[22:23], 0, v[204:205]
	s_add_i32 m0, s0, 0x400
	s_nop 0
	global_load_lds_dwordx4 v[254:255], off
	s_mov_b32 s0, 0x8000
	s_add_i32 s33, s66, s0
	v_lshl_add_u64 v[254:255], s[22:23], 0, v[202:203]
	s_mov_b64 s[0:1], 0x33e08000
	v_lshl_add_u64 v[254:255], v[254:255], 0, s[0:1]
	s_add_i32 m0, s33, 0x8000
	s_mov_b64 s[0:1], 0x80
	global_load_lds_dwordx4 v[254:255], off
	v_lshl_add_u64 v[254:255], v[254:255], 0, s[0:1]
	s_add_i32 m0, s33, 0x8400
	s_mov_b64 s[0:1], 0x780
	global_load_lds_dwordx4 v[254:255], off
	v_lshl_add_u64 v[254:255], v[254:255], 0, s[0:1]
	s_add_i32 m0, s33, 0x8800
	s_mov_b64 s[0:1], 0x80
	global_load_lds_dwordx4 v[254:255], off
	v_lshl_add_u64 v[254:255], v[254:255], 0, s[0:1]
	s_add_i32 m0, s33, 0x8c00
	s_nop 0
	global_load_lds_dwordx4 v[254:255], off
	s_barrier
	s_branch .Lpl_top
; #define SBAR() __builtin_amdgcn_sched_barrier(0)
; template <bool WIN>
; __device__ __forceinline__ void partialSM(f32x16& p0, f32x16& p1, float& m_reg, float& mn, float& alpha) {
;   constexpr float C = SCALE * 1.4426950408889634f;
;   float pmax = p0[0];
; #pragma unroll
;   for (int r = 1; r < 16; ++r) pmax = fmaxf(pmax, p0[r]);
; #pragma unroll
;   for (int r = 0; r < 16; ++r) pmax = fmaxf(pmax, p1[r]);
;   { auto rr = __builtin_amdgcn_permlane32_swap(__float_as_uint(pmax), __float_as_uint(pmax), false, false);
;     pmax = fmaxf(__uint_as_float(rr[0]), __uint_as_float(rr[1])); }
;   if (__builtin_expect(__all(pmax - m_reg <= THR / SCALE), 1)) { mn = m_reg; alpha = 1.f; }
;   else { mn = fmaxf(m_reg, pmax); alpha = __builtin_amdgcn_exp2f((m_reg - mn) * C); m_reg = mn; }
;   float mnC = -mn * C;
; #pragma unroll
;   for (int r = 0; r < 16; ++r) p0[r] = fmaf(p0[r], C, mnC);
; #pragma unroll
;   for (int r = 0; r < 16; ++r) p1[r] = fmaf(p1[r], C, mnC);
; template <int LDO>
; __device__ __forceinline__ void attn_unit_dv(const bf16_t* __restrict__ Qb, const bf16_t* __restrict__ Kh, const bf16_t* __restrict__ Vh, bf16_t* __restrict__ Ob, int NT, char* lds, LAS3 unsigned char* ldsl) {
;     ...
;   for (int t = 0; t < NT; ++t) {
;     const int buf = t & 1;
;     f32x16 p0, p1; float mn, alpha; bf16x8 pa0, pa1, pa2, pa3;
;     qkt<false>(p0, p1, (const bf16_t*)(lds + DV_K0 + buf * 16384), qr, r32, hi, 0);
;     SBAR();
;     if (t + 1 < NT) DMA_KV(t + 1, buf ^ 1);
;     SBAR();
;     partialSM<false>(p0, p1, m_reg, mn, alpha);
.Lpl_pre_e:
	s_mov_b32 s0, 0x8000
	s_add_i32 s33, s66, s0
	v_lshl_add_u64 v[254:255], s[22:23], 0, v[202:203]
	s_mov_b64 s[0:1], 0x33e08000
	v_lshl_add_u64 v[254:255], v[254:255], 0, s[0:1]
	s_add_i32 m0, s33, 0x8000
	s_mov_b64 s[0:1], 0x80
	global_load_lds_dwordx4 v[254:255], off
	v_lshl_add_u64 v[254:255], v[254:255], 0, s[0:1]
	s_add_i32 m0, s33, 0x8400
	s_mov_b64 s[0:1], 0x780
	global_load_lds_dwordx4 v[254:255], off
	v_lshl_add_u64 v[254:255], v[254:255], 0, s[0:1]
	s_add_i32 m0, s33, 0x8800
	s_mov_b64 s[0:1], 0x80
	global_load_lds_dwordx4 v[254:255], off
	v_lshl_add_u64 v[254:255], v[254:255], 0, s[0:1]
	s_add_i32 m0, s33, 0x8c00
	s_nop 0
	global_load_lds_dwordx4 v[254:255], off
.LBB0_643:
	s_and_b32 s69, s68, 1
	s_xor_b32 s33, s69, 1
	s_lshl_b32 s0, s33, 14
	s_add_i32 s0, s35, s0
	v_lshl_add_u64 v[254:255], s[22:23], 0, v[206:207]
	s_mov_b32 m0, s0
	s_nop 0
	global_load_lds_dwordx4 v[254:255], off
	v_lshl_add_u64 v[254:255], s[22:23], 0, v[204:205]
	s_add_i32 m0, s0, 0x400
	s_nop 0
	global_load_lds_dwordx4 v[254:255], off
	s_setprio 1
	s_lshl_b32 s0, s69, 14
	s_add_i32 s0, s0, 0
	v_add3_u32 v0, s0, v209, v199
	ds_read_b128 v[130:133], v0
	ds_read_b128 v[134:137], v0 offset:8192
	v_add3_u32 v0, s0, v210, v199
	ds_read_b128 v[232:235], v0
	ds_read_b128 v[236:239], v0 offset:8192
	v_add3_u32 v0, s0, v211, v199
	ds_read_b128 v[246:249], v0
	ds_read_b128 v[250:253], v0 offset:8192
	s_waitcnt lgkmcnt(4)
	v_mfma_f32_32x32x16_bf16 v[146:161], v[130:133], v[162:165], 0
	v_mfma_f32_32x32x16_bf16 v[130:145], v[134:137], v[162:165], 0
	s_waitcnt lgkmcnt(2)
	v_mfma_f32_32x32x16_bf16 v[146:161], v[232:235], v[166:169], v[146:161]
	v_mfma_f32_32x32x16_bf16 v[130:145], v[236:239], v[166:169], v[130:145]
	v_add3_u32 v0, s0, v212, v199
	ds_read_b128 v[232:235], v0
	ds_read_b128 v[236:239], v0 offset:8192
	s_waitcnt lgkmcnt(2)
	v_mfma_f32_32x32x16_bf16 v[146:161], v[246:249], v[170:173], v[146:161]
	v_mfma_f32_32x32x16_bf16 v[130:145], v[250:253], v[170:173], v[130:145]
	v_add3_u32 v0, s0, v213, v199
	ds_read_b128 v[246:249], v0
	ds_read_b128 v[250:253], v0 offset:8192
	s_waitcnt lgkmcnt(2)
	v_mfma_f32_32x32x16_bf16 v[146:161], v[232:235], v[174:177], v[146:161]
	v_mfma_f32_32x32x16_bf16 v[130:145], v[236:239], v[174:177], v[130:145]
	v_add3_u32 v0, s0, v214, v199
	ds_read_b128 v[232:235], v0
	ds_read_b128 v[236:239], v0 offset:8192
	s_waitcnt lgkmcnt(2)
	v_mfma_f32_32x32x16_bf16 v[146:161], v[246:249], v[178:181], v[146:161]
	v_mfma_f32_32x32x16_bf16 v[130:145], v[250:253], v[178:181], v[130:145]
	v_add3_u32 v0, s0, v215, v199
	ds_read_b128 v[246:249], v0
	ds_read_b128 v[250:253], v0 offset:8192
	s_waitcnt lgkmcnt(2)
	v_mfma_f32_32x32x16_bf16 v[146:161], v[232:235], v[182:185], v[146:161]
	v_mfma_f32_32x32x16_bf16 v[130:145], v[236:239], v[182:185], v[130:145]
	v_add3_u32 v0, s0, v216, v199
	ds_read_b128 v[232:235], v0
	ds_read_b128 v[236:239], v0 offset:8192
	s_waitcnt lgkmcnt(2)
	v_mfma_f32_32x32x16_bf16 v[146:161], v[246:249], v[186:189], v[146:161]
	v_mfma_f32_32x32x16_bf16 v[130:145], v[250:253], v[186:189], v[130:145]
	s_waitcnt lgkmcnt(0)
	v_mfma_f32_32x32x16_bf16 v[146:161], v[232:235], v[190:193], v[146:161]
	v_mfma_f32_32x32x16_bf16 v[130:145], v[236:239], v[190:193], v[130:145]
	s_setprio 0
	s_nop 7
	s_nop 3
	v_max_f32_e32 v0, v147, v147
	v_max_f32_e32 v231, v146, v146
	v_max_f32_e32 v0, v231, v0
	v_max3_f32 v0, v0, v148, v149
	v_max3_f32 v0, v0, v150, v151
	v_max3_f32 v0, v0, v152, v153
	v_max3_f32 v0, v0, v154, v155
	v_max3_f32 v0, v0, v156, v157
	v_max3_f32 v0, v0, v158, v159
	v_max3_f32 v0, v0, v160, v161
	v_max3_f32 v0, v0, v130, v131
	v_max3_f32 v0, v0, v132, v133
	v_max3_f32 v0, v0, v134, v135
	v_max3_f32 v0, v0, v136, v137
	v_max3_f32 v0, v0, v138, v139
	v_max3_f32 v0, v0, v140, v141
	v_max3_f32 v0, v0, v142, v143
	v_max3_f32 v0, v0, v144, v145
	v_mov_b32_e32 v231, v0
	s_nop 1
	v_permlane32_swap_b32_e32 v0, v231
	v_max_f32_e32 v231, v231, v231
	v_max_f32_e32 v0, v0, v0
	v_max_f32_e32 v0, v0, v231
	v_sub_f32_e32 v231, v0, v229
	s_mov_b32 s0, 0x42b504f3
	v_cmp_ge_f32_e32 vcc, s0, v231
	v_max_f32_e32 v232, v229, v229
	s_cmp_eq_u64 vcc, exec
	v_max_f32_e32 v232, v232, v0
	s_cselect_b64 vcc, -1, 0
	v_sub_f32_e32 v0, v229, v232
	v_cndmask_b32_e32 v229, v232, v229, vcc
	v_mul_f32_e32 v231, 0xbe0293ee, v229
	v_fmamk_f32 v146, v146, 0x3e0293ee, v231
	v_fmamk_f32 v147, v147, 0x3e0293ee, v231
	v_fmamk_f32 v148, v148, 0x3e0293ee, v231
	v_fmamk_f32 v149, v149, 0x3e0293ee, v231
	v_fmamk_f32 v150, v150, 0x3e0293ee, v231
	v_fmamk_f32 v151, v151, 0x3e0293ee, v231
	v_fmamk_f32 v152, v152, 0x3e0293ee, v231
	v_fmamk_f32 v153, v153, 0x3e0293ee, v231
	v_fmamk_f32 v154, v154, 0x3e0293ee, v231
	v_fmamk_f32 v155, v155, 0x3e0293ee, v231
	v_fmamk_f32 v156, v156, 0x3e0293ee, v231
	v_fmamk_f32 v157, v157, 0x3e0293ee, v231
	v_fmamk_f32 v158, v158, 0x3e0293ee, v231
	v_fmamk_f32 v159, v159, 0x3e0293ee, v231
	v_fmamk_f32 v160, v160, 0x3e0293ee, v231
	v_fmamk_f32 v161, v161, 0x3e0293ee, v231
	v_fmamk_f32 v130, v130, 0x3e0293ee, v231
	v_fmamk_f32 v131, v131, 0x3e0293ee, v231
	v_fmamk_f32 v132, v132, 0x3e0293ee, v231
	v_fmamk_f32 v133, v133, 0x3e0293ee, v231
	v_fmamk_f32 v134, v134, 0x3e0293ee, v231
	v_fmamk_f32 v135, v135, 0x3e0293ee, v231
	v_fmamk_f32 v136, v136, 0x3e0293ee, v231
	v_fmamk_f32 v137, v137, 0x3e0293ee, v231
	v_fmamk_f32 v138, v138, 0x3e0293ee, v231
	v_fmamk_f32 v139, v139, 0x3e0293ee, v231
	v_fmamk_f32 v140, v140, 0x3e0293ee, v231
	v_fmamk_f32 v141, v141, 0x3e0293ee, v231
	v_fmamk_f32 v142, v142, 0x3e0293ee, v231
	v_fmamk_f32 v143, v143, 0x3e0293ee, v231
	v_fmamk_f32 v144, v144, 0x3e0293ee, v231
	v_fmac_f32_e32 v231, 0x3e0293ee, v145
; __device__ __forceinline__ void finishSM(f32x16& p0, f32x16& p1, float alpha, float& l_reg, bf16x8& pa0, bf16x8& pa1, bf16x8& pa2, bf16x8& pa3) {
; #pragma unroll
;   for (int r = 0; r < 16; ++r) p1[r] = __builtin_amdgcn_exp2f(p1[r]);
;   float ps = 0;
; #pragma unroll
;   for (int r = 0; r < 16; ++r) ps += p0[r];
; #pragma unroll
;   for (int r = 0; r < 16; ++r) ps += p1[r];
;   { auto rr = __builtin_amdgcn_permlane32_swap(__float_as_uint(ps), __float_as_uint(ps), false, false);
;     ps = __uint_as_float(rr[0]) + __uint_as_float(rr[1]); }
;   l_reg = l_reg * alpha + ps;
;     ...
;   PK4(p0, 0, pa0); PK4(p0, 8, pa1); PK4(p1, 0, pa2); PK4(p1, 8, pa3);
	v_exp_f32_e32 v145, v146
	v_exp_f32_e32 v146, v147
	v_exp_f32_e32 v147, v148
	v_exp_f32_e32 v148, v149
	v_exp_f32_e32 v149, v150
	v_exp_f32_e32 v150, v151
	v_exp_f32_e32 v151, v152
	v_exp_f32_e32 v152, v153
	v_exp_f32_e32 v153, v154
	v_exp_f32_e32 v154, v155
	v_exp_f32_e32 v155, v156
	v_exp_f32_e32 v156, v157
	v_exp_f32_e32 v157, v158
	v_exp_f32_e32 v158, v159
	v_exp_f32_e32 v159, v160
	v_exp_f32_e32 v160, v161
	v_exp_f32_e32 v161, v134
	v_add_f32_e32 v134, 0, v145
	v_add_f32_e32 v134, v146, v134
	v_add_f32_e32 v134, v147, v134
	v_add_f32_e32 v134, v148, v134
	v_add_f32_e32 v134, v149, v134
	v_add_f32_e32 v134, v150, v134
	v_add_f32_e32 v134, v151, v134
	v_add_f32_e32 v134, v152, v134
	v_add_f32_e32 v134, v153, v134
	v_add_f32_e32 v134, v154, v134
	v_add_f32_e32 v134, v155, v134
	v_add_f32_e32 v134, v156, v134
	v_exp_f32_e32 v130, v130
	v_add_f32_e32 v134, v157, v134
	v_exp_f32_e32 v131, v131
	v_add_f32_e32 v134, v158, v134
	v_exp_f32_e32 v132, v132
	v_add_f32_e32 v134, v159, v134
	v_exp_f32_e32 v133, v133
	v_add_f32_e32 v134, v160, v134
	v_add_f32_e32 v134, v130, v134
	v_exp_f32_e32 v233, v135
	v_add_f32_e32 v134, v131, v134
	v_exp_f32_e32 v234, v136
	v_add_f32_e32 v134, v132, v134
	v_exp_f32_e32 v235, v137
	v_add_f32_e32 v134, v133, v134
	v_exp_f32_e32 v138, v138
	v_add_f32_e32 v134, v161, v134
	v_exp_f32_e32 v139, v139
	v_add_f32_e32 v134, v233, v134
	v_exp_f32_e32 v140, v140
	v_add_f32_e32 v134, v234, v134
	v_exp_f32_e32 v141, v141
	v_add_f32_e32 v134, v235, v134
	v_exp_f32_e32 v236, v142
	v_add_f32_e32 v134, v138, v134
	v_exp_f32_e32 v237, v143
	v_add_f32_e32 v134, v139, v134
	v_exp_f32_e32 v238, v144
	v_add_f32_e32 v134, v140, v134
	v_mul_f32_e32 v0, 0x3e0293ee, v0
	v_exp_f32_e32 v239, v231
	v_add_f32_e32 v134, v141, v134
	v_exp_f32_e32 v0, v0
	v_add_f32_e32 v134, v236, v134
	v_add_f32_e32 v134, v237, v134
	v_add_f32_e32 v134, v238, v134
	v_add_f32_e32 v231, v239, v134
	v_cndmask_b32_e64 v0, v0, 1.0, vcc
	v_mov_b32_e32 v232, v231
	v_cvt_pk_bf16_f32 v134, v145, v146
	v_cvt_pk_bf16_f32 v135, v147, v148
	v_cvt_pk_bf16_f32 v136, v149, v150
	v_cvt_pk_bf16_f32 v137, v151, v152
	v_cvt_pk_bf16_f32 v142, v153, v154
	v_cvt_pk_bf16_f32 v143, v155, v156
	v_cvt_pk_bf16_f32 v144, v157, v158
	v_cvt_pk_bf16_f32 v145, v159, v160
	v_cvt_pk_bf16_f32 v130, v130, v131
	v_cvt_pk_bf16_f32 v131, v132, v133
	v_cvt_pk_bf16_f32 v132, v161, v233
	v_cvt_pk_bf16_f32 v133, v234, v235
	v_cvt_pk_bf16_f32 v138, v138, v139
	v_cvt_pk_bf16_f32 v139, v140, v141
	v_cvt_pk_bf16_f32 v140, v236, v237
	v_cvt_pk_bf16_f32 v141, v238, v239
	v_permlane32_swap_b32_e32 v231, v232
	v_permlane32_swap_b32_e32 v134, v136
	v_permlane32_swap_b32_e32 v135, v137
	v_permlane32_swap_b32_e32 v142, v144
	v_permlane32_swap_b32_e32 v143, v145
	v_permlane32_swap_b32_e32 v130, v132
	v_permlane32_swap_b32_e32 v131, v133
	v_permlane32_swap_b32_e32 v138, v140
	v_permlane32_swap_b32_e32 v139, v141
	v_cmp_gt_f32_e32 vcc, 1.0, v0
	s_cbranch_vccz .LBB0_649
	s_and_saveexec_b64 s[0:1], s[6:7]
	ds_write_b32 v228, v0 offset:128
	s_or_b64 exec, exec, s[0:1]
	s_waitcnt lgkmcnt(0)
	v_add_u32_e32 v146, s67, v223
	ds_read_b128 v[158:161], v146 offset:224
	ds_read_b128 v[154:157], v146 offset:192
	ds_read_b128 v[150:153], v146 offset:160
	ds_read_b128 v[146:149], v146 offset:128
	s_waitcnt lgkmcnt(0)
	v_pk_mul_f32 v[126:127], v[126:127], v[158:159]
	v_pk_mul_f32 v[122:123], v[122:123], v[154:155]
	v_pk_mul_f32 v[118:119], v[118:119], v[150:151]
	v_pk_mul_f32 v[128:129], v[128:129], v[160:161]
	v_pk_mul_f32 v[124:125], v[124:125], v[156:157]
	v_pk_mul_f32 v[120:121], v[120:121], v[152:153]
	v_pk_mul_f32 v[116:117], v[116:117], v[148:149]
	v_pk_mul_f32 v[114:115], v[114:115], v[146:147]
	v_pk_mul_f32 v[110:111], v[110:111], v[158:159]
	v_pk_mul_f32 v[106:107], v[106:107], v[154:155]
	v_pk_mul_f32 v[102:103], v[102:103], v[150:151]
	v_pk_mul_f32 v[112:113], v[112:113], v[160:161]
	v_pk_mul_f32 v[108:109], v[108:109], v[156:157]
	v_pk_mul_f32 v[104:105], v[104:105], v[152:153]
	v_pk_mul_f32 v[100:101], v[100:101], v[148:149]
	v_pk_mul_f32 v[98:99], v[98:99], v[146:147]
	v_pk_mul_f32 v[94:95], v[94:95], v[158:159]
	v_pk_mul_f32 v[90:91], v[90:91], v[154:155]
	v_pk_mul_f32 v[86:87], v[86:87], v[150:151]
	v_pk_mul_f32 v[96:97], v[96:97], v[160:161]
	v_pk_mul_f32 v[92:93], v[92:93], v[156:157]
	v_pk_mul_f32 v[88:89], v[88:89], v[152:153]
	v_pk_mul_f32 v[84:85], v[84:85], v[148:149]
	v_pk_mul_f32 v[82:83], v[82:83], v[146:147]
	v_pk_mul_f32 v[78:79], v[78:79], v[158:159]
	v_pk_mul_f32 v[74:75], v[74:75], v[154:155]
	v_pk_mul_f32 v[70:71], v[70:71], v[150:151]
	v_pk_mul_f32 v[80:81], v[80:81], v[160:161]
	v_pk_mul_f32 v[76:77], v[76:77], v[156:157]
	v_pk_mul_f32 v[72:73], v[72:73], v[152:153]
	v_pk_mul_f32 v[68:69], v[68:69], v[148:149]
	v_pk_mul_f32 v[66:67], v[66:67], v[146:147]
	v_pk_mul_f32 v[62:63], v[62:63], v[158:159]
	v_pk_mul_f32 v[58:59], v[58:59], v[154:155]
	v_pk_mul_f32 v[54:55], v[54:55], v[150:151]
	v_pk_mul_f32 v[64:65], v[64:65], v[160:161]
	v_pk_mul_f32 v[60:61], v[60:61], v[156:157]
	v_pk_mul_f32 v[56:57], v[56:57], v[152:153]
	v_pk_mul_f32 v[52:53], v[52:53], v[148:149]
	v_pk_mul_f32 v[50:51], v[50:51], v[146:147]
	v_pk_mul_f32 v[46:47], v[46:47], v[158:159]
	v_pk_mul_f32 v[42:43], v[42:43], v[154:155]
	v_pk_mul_f32 v[38:39], v[38:39], v[150:151]
	v_pk_mul_f32 v[48:49], v[48:49], v[160:161]
	v_pk_mul_f32 v[44:45], v[44:45], v[156:157]
	v_pk_mul_f32 v[40:41], v[40:41], v[152:153]
	v_pk_mul_f32 v[36:37], v[36:37], v[148:149]
	v_pk_mul_f32 v[34:35], v[34:35], v[146:147]
	v_pk_mul_f32 v[30:31], v[30:31], v[158:159]
	v_pk_mul_f32 v[26:27], v[26:27], v[154:155]
	v_pk_mul_f32 v[22:23], v[22:23], v[150:151]
	v_pk_mul_f32 v[32:33], v[32:33], v[160:161]
	v_pk_mul_f32 v[28:29], v[28:29], v[156:157]
	v_pk_mul_f32 v[24:25], v[24:25], v[152:153]
	v_pk_mul_f32 v[20:21], v[20:21], v[148:149]
	v_pk_mul_f32 v[18:19], v[18:19], v[146:147]
	v_pk_mul_f32 v[14:15], v[14:15], v[158:159]
	v_pk_mul_f32 v[10:11], v[10:11], v[154:155]
	v_pk_mul_f32 v[6:7], v[6:7], v[150:151]
	v_pk_mul_f32 v[16:17], v[16:17], v[160:161]
	v_pk_mul_f32 v[12:13], v[12:13], v[156:157]
	v_pk_mul_f32 v[8:9], v[8:9], v[152:153]
	v_pk_mul_f32 v[4:5], v[4:5], v[148:149]
	v_pk_mul_f32 v[2:3], v[2:3], v[146:147]
; #define SBAR() __builtin_amdgcn_sched_barrier(0)
; #define RESC8(a) do { if (__any((a) < 1.f)) { if (hi == 0) al_l[r32] = (a); asm volatile("s_waitcnt lgkmcnt(0)" ::: "memory"); \
;     _Pragma("unroll") for (int d = 0; d < 8; ++d) _Pragma("unroll") for (int r = 0; r < 16; ++r) o[d][r] *= al_l[crow(r, hi)]; } } while (0)
; template <int D0> __device__ __forceinline__ void pv_one(f32x16& od, int vb, bf16x8 pa0, bf16x8 pa1, bf16x8 pa2, bf16x8 pa3) {
;   const s16x4 l0 = tr_read<v_rd_off(D0, 0, 0)>(vb), h0 = tr_read<v_rd_off(D0, 0, 1)>(vb), l1 = tr_read<v_rd_off(D0, 1, 0)>(vb), h1 = tr_read<v_rd_off(D0, 1, 1)>(vb);
;   const s16x4 l2 = tr_read<v_rd_off(D0, 2, 0)>(vb), h2 = tr_read<v_rd_off(D0, 2, 1)>(vb), l3 = tr_read<v_rd_off(D0, 3, 0)>(vb), h3 = tr_read<v_rd_off(D0, 3, 1)>(vb);
;   asm volatile("s_waitcnt lgkmcnt(0)" ::: "memory"); SBAR();
;     ...
;   od = __builtin_amdgcn_mfma_f32_32x32x16_bf16(pa0, PK(l0, h0), od, 0, 0, 0);
;   od = __builtin_amdgcn_mfma_f32_32x32x16_bf16(pa1, PK(l1, h1), od, 0, 0, 0);
;   od = __builtin_amdgcn_mfma_f32_32x32x16_bf16(pa2, PK(l2, h2), od, 0, 0, 0);
;   od = __builtin_amdgcn_mfma_f32_32x32x16_bf16(pa3, PK(l3, h3), od, 0, 0, 0);
;     ...
; }
; __device__ __forceinline__ void pv_d0(f32x16* o, int vb, bf16x8 pa0, bf16x8 pa1, bf16x8 pa2, bf16x8 pa3) {
;   pv_one<0>(o[0], vb, pa0, pa1, pa2, pa3); pv_one<1>(o[1], vb, pa0, pa1, pa2, pa3); pv_one<2>(o[2], vb, pa0, pa1, pa2, pa3); pv_one<3>(o[3], vb, pa0, pa1, pa2, pa3);
; }
; template <int LDO>
; __device__ __forceinline__ void attn_unit_dv(const bf16_t* __restrict__ Qb, const bf16_t* __restrict__ Kh, const bf16_t* __restrict__ Vh, bf16_t* __restrict__ Ob, int NT, char* lds, LAS3 unsigned char* ldsl) {
;     ...
;   for (int t = 0; t < NT; ++t) {
;     const int buf = t & 1;
;     f32x16 p0, p1; float mn, alpha; bf16x8 pa0, pa1, pa2, pa3;
;     qkt<false>(p0, p1, (const bf16_t*)(lds + DV_K0 + buf * 16384), qr, r32, hi, 0);
;     SBAR();
;     if (t + 1 < NT) DMA_KV(t + 1, buf ^ 1);
;     SBAR();
;     partialSM<false>(p0, p1, m_reg, mn, alpha);
;     finishSM(p0, p1, alpha, l_reg, pa0, pa1, pa2, pa3);
;     RESC8(alpha);
;     SBAR();
;     pv_d0(o, vb0 + buf * 32768, pa0, pa1, pa2, pa3);
;     pv_d0(o + 4, vb0 + buf * 32768 + 16384, pa0, pa1, pa2, pa3);
;     asm volatile("s_waitcnt vmcnt(0) lgkmcnt(0)" ::: "memory"); __builtin_amdgcn_s_barrier(); asm volatile("" ::: "memory");
.LBB0_649:
	s_waitcnt vmcnt(6)
	s_barrier
	s_lshl_b32 s0, s101, 15
	s_add_i32 s33, s66, s0
	v_lshl_add_u64 v[254:255], s[22:23], 0, v[202:203]
	s_mov_b64 s[0:1], 0x33e10000
	v_lshl_add_u64 v[254:255], v[254:255], 0, s[0:1]
	s_add_i32 m0, s33, 0x8000
	s_mov_b64 s[0:1], 0x80
	global_load_lds_dwordx4 v[254:255], off
	v_lshl_add_u64 v[254:255], v[254:255], 0, s[0:1]
	s_add_i32 m0, s33, 0x8400
	s_mov_b64 s[0:1], 0x780
	global_load_lds_dwordx4 v[254:255], off
	v_lshl_add_u64 v[254:255], v[254:255], 0, s[0:1]
	s_add_i32 m0, s33, 0x8800
	s_mov_b64 s[0:1], 0x80
	global_load_lds_dwordx4 v[254:255], off
	v_lshl_add_u64 v[254:255], v[254:255], 0, s[0:1]
	s_add_i32 m0, s33, 0x8c00
	s_nop 0
	global_load_lds_dwordx4 v[254:255], off
	v_add_f32_e32 v146, v231, v232
	v_fmac_f32_e32 v146, v230, v0
	s_add_i32 s68, s68, 1
	v_lshl_add_u32 v0, s98, 15, v224
	ds_read_b64_tr_b16 v[148:149], v0 offset:0
	ds_read_b64_tr_b16 v[150:151], v0 offset:0x800
	ds_read_b64_tr_b16 v[152:153], v0 offset:0x1000
	ds_read_b64_tr_b16 v[154:155], v0 offset:0x1800
	ds_read_b64_tr_b16 v[156:157], v0 offset:0x2000
	ds_read_b64_tr_b16 v[158:159], v0 offset:0x2800
	ds_read_b64_tr_b16 v[230:231], v0 offset:0x3000
	ds_read_b64_tr_b16 v[232:233], v0 offset:0x3800
	s_waitcnt lgkmcnt(0)
	s_nop 0
	v_mfma_f32_32x32x16_bf16 v[114:129], v[134:137], v[148:151], v[114:129]
	ds_read_b64_tr_b16 v[148:149], v0 offset:0x200
	ds_read_b64_tr_b16 v[150:151], v0 offset:0xa00
	v_mfma_f32_32x32x16_bf16 v[114:129], v[142:145], v[152:155], v[114:129]
	ds_read_b64_tr_b16 v[152:153], v0 offset:0x1200
	ds_read_b64_tr_b16 v[154:155], v0 offset:0x1a00
	v_mfma_f32_32x32x16_bf16 v[114:129], v[130:133], v[156:159], v[114:129]
	ds_read_b64_tr_b16 v[156:157], v0 offset:0x2200
	ds_read_b64_tr_b16 v[158:159], v0 offset:0x2a00
	ds_read_b64_tr_b16 v[234:235], v0 offset:0x3200
	ds_read_b64_tr_b16 v[236:237], v0 offset:0x3a00
	s_waitcnt lgkmcnt(0)
	v_mfma_f32_32x32x16_bf16 v[114:129], v[138:141], v[230:233], v[114:129]
	v_mfma_f32_32x32x16_bf16 v[98:113], v[134:137], v[148:151], v[98:113]
	ds_read_b64_tr_b16 v[148:149], v0 offset:0x400
	ds_read_b64_tr_b16 v[150:151], v0 offset:0xc00
	v_mfma_f32_32x32x16_bf16 v[98:113], v[142:145], v[152:155], v[98:113]
	ds_read_b64_tr_b16 v[152:153], v0 offset:0x1400
	ds_read_b64_tr_b16 v[154:155], v0 offset:0x1c00
	v_mfma_f32_32x32x16_bf16 v[98:113], v[130:133], v[156:159], v[98:113]
	ds_read_b64_tr_b16 v[156:157], v0 offset:0x2400
	ds_read_b64_tr_b16 v[158:159], v0 offset:0x2c00
	ds_read_b64_tr_b16 v[230:231], v0 offset:0x3400
	ds_read_b64_tr_b16 v[232:233], v0 offset:0x3c00
	s_waitcnt lgkmcnt(0)
	v_mfma_f32_32x32x16_bf16 v[98:113], v[138:141], v[234:237], v[98:113]
	v_mfma_f32_32x32x16_bf16 v[82:97], v[134:137], v[148:151], v[82:97]
	ds_read_b64_tr_b16 v[148:149], v0 offset:0x600
	ds_read_b64_tr_b16 v[150:151], v0 offset:0xe00
	v_mfma_f32_32x32x16_bf16 v[82:97], v[142:145], v[152:155], v[82:97]
	ds_read_b64_tr_b16 v[152:153], v0 offset:0x1600
	ds_read_b64_tr_b16 v[154:155], v0 offset:0x1e00
	v_mfma_f32_32x32x16_bf16 v[82:97], v[130:133], v[156:159], v[82:97]
	ds_read_b64_tr_b16 v[156:157], v0 offset:0x2600
	ds_read_b64_tr_b16 v[158:159], v0 offset:0x2e00
	ds_read_b64_tr_b16 v[234:235], v0 offset:0x3600
	ds_read_b64_tr_b16 v[236:237], v0 offset:0x3e00
	s_waitcnt lgkmcnt(0)
	v_mfma_f32_32x32x16_bf16 v[82:97], v[138:141], v[230:233], v[82:97]
	v_mfma_f32_32x32x16_bf16 v[66:81], v[134:137], v[148:151], v[66:81]
	v_add_u32_e32 v0, 0x4000, v0
	ds_read_b64_tr_b16 v[148:149], v0 offset:0
	ds_read_b64_tr_b16 v[150:151], v0 offset:0x800
	v_mfma_f32_32x32x16_bf16 v[66:81], v[142:145], v[152:155], v[66:81]
	ds_read_b64_tr_b16 v[152:153], v0 offset:0x1000
	ds_read_b64_tr_b16 v[154:155], v0 offset:0x1800
	v_mfma_f32_32x32x16_bf16 v[66:81], v[130:133], v[156:159], v[66:81]
	ds_read_b64_tr_b16 v[156:157], v0 offset:0x2000
	ds_read_b64_tr_b16 v[158:159], v0 offset:0x2800
	ds_read_b64_tr_b16 v[230:231], v0 offset:0x3000
	ds_read_b64_tr_b16 v[232:233], v0 offset:0x3800
	s_waitcnt lgkmcnt(0)
	v_mfma_f32_32x32x16_bf16 v[66:81], v[138:141], v[234:237], v[66:81]
	v_mfma_f32_32x32x16_bf16 v[50:65], v[134:137], v[148:151], v[50:65]
	ds_read_b64_tr_b16 v[148:149], v0 offset:0x200
	ds_read_b64_tr_b16 v[150:151], v0 offset:0xa00
	v_mfma_f32_32x32x16_bf16 v[50:65], v[142:145], v[152:155], v[50:65]
	ds_read_b64_tr_b16 v[152:153], v0 offset:0x1200
	ds_read_b64_tr_b16 v[154:155], v0 offset:0x1a00
	v_mfma_f32_32x32x16_bf16 v[50:65], v[130:133], v[156:159], v[50:65]
	ds_read_b64_tr_b16 v[156:157], v0 offset:0x2200
	ds_read_b64_tr_b16 v[158:159], v0 offset:0x2a00
	ds_read_b64_tr_b16 v[234:235], v0 offset:0x3200
	ds_read_b64_tr_b16 v[236:237], v0 offset:0x3a00
	s_waitcnt lgkmcnt(0)
	v_mfma_f32_32x32x16_bf16 v[50:65], v[138:141], v[230:233], v[50:65]
	v_mfma_f32_32x32x16_bf16 v[34:49], v[134:137], v[148:151], v[34:49]
	ds_read_b64_tr_b16 v[148:149], v0 offset:0x400
	ds_read_b64_tr_b16 v[150:151], v0 offset:0xc00
	v_mfma_f32_32x32x16_bf16 v[34:49], v[142:145], v[152:155], v[34:49]
	ds_read_b64_tr_b16 v[152:153], v0 offset:0x1400
	ds_read_b64_tr_b16 v[154:155], v0 offset:0x1c00
	v_mfma_f32_32x32x16_bf16 v[34:49], v[130:133], v[156:159], v[34:49]
	ds_read_b64_tr_b16 v[156:157], v0 offset:0x2400
	ds_read_b64_tr_b16 v[158:159], v0 offset:0x2c00
	ds_read_b64_tr_b16 v[230:231], v0 offset:0x3400
	ds_read_b64_tr_b16 v[232:233], v0 offset:0x3c00
	s_waitcnt lgkmcnt(0)
	v_mfma_f32_32x32x16_bf16 v[34:49], v[138:141], v[234:237], v[34:49]
	v_mfma_f32_32x32x16_bf16 v[18:33], v[134:137], v[148:151], v[18:33]
	ds_read_b64_tr_b16 v[148:149], v0 offset:0x600
	ds_read_b64_tr_b16 v[150:151], v0 offset:0xe00
	v_mfma_f32_32x32x16_bf16 v[18:33], v[142:145], v[152:155], v[18:33]
	ds_read_b64_tr_b16 v[152:153], v0 offset:0x1600
	ds_read_b64_tr_b16 v[154:155], v0 offset:0x1e00
	v_mfma_f32_32x32x16_bf16 v[18:33], v[130:133], v[156:159], v[18:33]
	ds_read_b64_tr_b16 v[156:157], v0 offset:0x2600
	ds_read_b64_tr_b16 v[158:159], v0 offset:0x2e00
	ds_read_b64_tr_b16 v[234:235], v0 offset:0x3600
	ds_read_b64_tr_b16 v[236:237], v0 offset:0x3e00
	s_waitcnt lgkmcnt(0)
	v_mfma_f32_32x32x16_bf16 v[18:33], v[138:141], v[230:233], v[18:33]
	v_mfma_f32_32x32x16_bf16 v[2:17], v[134:137], v[148:151], v[2:17]
	s_waitcnt vmcnt(4) lgkmcnt(0)
	s_barrier
	s_mov_b32 s98, s100
	s_mov_b32 s100, s101
	s_add_i32 s101, s101, 1
	s_cmp_eq_u32 s101, 3
	s_cselect_b32 s101, 0, s101
	s_mov_b64 s[0:1], 0x8000
	v_lshl_add_u64 v[202:203], v[202:203], 0, s[0:1]
	v_lshl_add_u64 v[204:205], v[204:205], 0, s[64:65]
	v_lshl_add_u64 v[206:207], v[206:207], 0, s[64:65]
	v_mfma_f32_32x32x16_bf16 v[2:17], v[142:145], v[152:155], v[2:17]
	s_cmpk_eq_i32 s68, 0x100
	v_mfma_f32_32x32x16_bf16 v[2:17], v[130:133], v[156:159], v[2:17]
	v_mfma_f32_32x32x16_bf16 v[2:17], v[138:141], v[234:237], v[2:17]
	s_cbranch_scc1 .LBB0_651
	v_mov_b32_e32 v230, v146
	s_branch .LBB0_643
; template <bool WIN>
; __device__ __forceinline__ void partialSM(f32x16& p0, f32x16& p1, float& m_reg, float& mn, float& alpha) {
;   constexpr float C = SCALE * 1.4426950408889634f;
;   float pmax = p0[0];
; #pragma unroll
;   for (int r = 1; r < 16; ++r) pmax = fmaxf(pmax, p0[r]);
; #pragma unroll
;   for (int r = 0; r < 16; ++r) pmax = fmaxf(pmax, p1[r]);
;   { auto rr = __builtin_amdgcn_permlane32_swap(__float_as_uint(pmax), __float_as_uint(pmax), false, false);
;     pmax = fmaxf(__uint_as_float(rr[0]), __uint_as_float(rr[1])); }
;   if (__builtin_expect(__all(pmax - m_reg <= THR / SCALE), 1)) { mn = m_reg; alpha = 1.f; }
;   else { mn = fmaxf(m_reg, pmax); alpha = __builtin_amdgcn_exp2f((m_reg - mn) * C); m_reg = mn; }
;   float mnC = -mn * C;
; #pragma unroll
;   for (int r = 0; r < 16; ++r) p0[r] = fmaf(p0[r], C, mnC);
; #pragma unroll
;   for (int r = 0; r < 16; ++r) p1[r] = fmaf(p1[r], C, mnC);
; template <bool WIN>
; __device__ __forceinline__ void qkt(f32x16& p0, f32x16& p1, const bf16_t* Ks, const bf16x8* qr, int r32, int hi, int dq) {
;   p0 = f32x16{}; p1 = f32x16{};
;   if (WIN) {
;     const int t = 4 * hi - dq + 128;
; #pragma unroll
;     for (int r = 0; r < 16; ++r) { const unsigned d0 = (unsigned)(t + (r & 3) + 8 * (r >> 2)), d1 = d0 + 32u;
;       p0[r] = d0 > 256u ? -1e30f : 0.f; p1[r] = d1 > 256u ? -1e30f : 0.f; }
;   }
; #pragma unroll
;   for (int d0 = 0; d0 < 8; ++d0) { int cb = (d0 * 16 + hi * 8) * 2;
;     bf16x8 b0 = *reinterpret_cast<const bf16x8*>((const char*)Ks + KSWZ(r32, cb));
;     bf16x8 b1 = *reinterpret_cast<const bf16x8*>((const char*)Ks + KSWZ(32 + r32, cb));
;     p0 = __builtin_amdgcn_mfma_f32_32x32x16_bf16(b0, qr[d0], p0, 0, 0, 0);
;     p1 = __builtin_amdgcn_mfma_f32_32x32x16_bf16(b1, qr[d0], p1, 0, 0, 0); }
.Lpl_top:
	s_and_b32 s69, s68, 1
	s_setprio 1
	s_lshl_b32 s0, s69, 14
	s_add_i32 s0, s0, 0
	v_add3_u32 v0, s0, v209, v199
	ds_read_b128 v[130:133], v0
	ds_read_b128 v[134:137], v0 offset:8192
	v_add3_u32 v0, s0, v210, v199
	ds_read_b128 v[232:235], v0
	ds_read_b128 v[236:239], v0 offset:8192
	v_add3_u32 v0, s0, v211, v199
	ds_read_b128 v[246:249], v0
	ds_read_b128 v[250:253], v0 offset:8192
	s_waitcnt lgkmcnt(4)
	v_mfma_f32_32x32x16_bf16 v[146:161], v[130:133], v[162:165], 0
	v_mfma_f32_32x32x16_bf16 v[130:145], v[134:137], v[162:165], 0
	s_waitcnt lgkmcnt(2)
	v_mfma_f32_32x32x16_bf16 v[146:161], v[232:235], v[166:169], v[146:161]
	v_mfma_f32_32x32x16_bf16 v[130:145], v[236:239], v[166:169], v[130:145]
	v_add3_u32 v0, s0, v212, v199
	ds_read_b128 v[232:235], v0
	ds_read_b128 v[236:239], v0 offset:8192
	s_waitcnt lgkmcnt(2)
	v_mfma_f32_32x32x16_bf16 v[146:161], v[246:249], v[170:173], v[146:161]
	v_mfma_f32_32x32x16_bf16 v[130:145], v[250:253], v[170:173], v[130:145]
	v_add3_u32 v0, s0, v213, v199
	ds_read_b128 v[246:249], v0
	ds_read_b128 v[250:253], v0 offset:8192
	s_waitcnt lgkmcnt(2)
	v_mfma_f32_32x32x16_bf16 v[146:161], v[232:235], v[174:177], v[146:161]
	v_mfma_f32_32x32x16_bf16 v[130:145], v[236:239], v[174:177], v[130:145]
	v_add3_u32 v0, s0, v214, v199
	ds_read_b128 v[232:235], v0
	ds_read_b128 v[236:239], v0 offset:8192
	s_waitcnt lgkmcnt(2)
	v_mfma_f32_32x32x16_bf16 v[146:161], v[246:249], v[178:181], v[146:161]
	v_mfma_f32_32x32x16_bf16 v[130:145], v[250:253], v[178:181], v[130:145]
	v_add3_u32 v0, s0, v215, v199
	ds_read_b128 v[246:249], v0
	ds_read_b128 v[250:253], v0 offset:8192
	s_waitcnt lgkmcnt(2)
	v_mfma_f32_32x32x16_bf16 v[146:161], v[232:235], v[182:185], v[146:161]
	v_mfma_f32_32x32x16_bf16 v[130:145], v[236:239], v[182:185], v[130:145]
	v_add3_u32 v0, s0, v216, v199
	ds_read_b128 v[232:235], v0
	ds_read_b128 v[236:239], v0 offset:8192
	s_waitcnt lgkmcnt(2)
	v_mfma_f32_32x32x16_bf16 v[146:161], v[246:249], v[186:189], v[146:161]
	v_mfma_f32_32x32x16_bf16 v[130:145], v[250:253], v[186:189], v[130:145]
	s_waitcnt lgkmcnt(0)
	v_mfma_f32_32x32x16_bf16 v[146:161], v[232:235], v[190:193], v[146:161]
	v_mfma_f32_32x32x16_bf16 v[130:145], v[236:239], v[190:193], v[130:145]
	s_setprio 0
	s_nop 7
	s_nop 3
	v_max_f32_e32 v0, v147, v147
	v_max_f32_e32 v231, v146, v146
	v_max_f32_e32 v0, v231, v0
	v_max3_f32 v0, v0, v148, v149
	v_max3_f32 v0, v0, v150, v151
	v_max3_f32 v0, v0, v152, v153
	v_max3_f32 v0, v0, v154, v155
	v_max3_f32 v0, v0, v156, v157
	v_max3_f32 v0, v0, v158, v159
	v_max3_f32 v0, v0, v160, v161
	v_max3_f32 v0, v0, v130, v131
	v_max3_f32 v0, v0, v132, v133
	v_max3_f32 v0, v0, v134, v135
	v_max3_f32 v0, v0, v136, v137
	v_max3_f32 v0, v0, v138, v139
	v_max3_f32 v0, v0, v140, v141
	v_max3_f32 v0, v0, v142, v143
	v_max3_f32 v0, v0, v144, v145
	v_mov_b32_e32 v231, v0
	s_nop 1
	v_permlane32_swap_b32_e32 v0, v231
	v_max_f32_e32 v231, v231, v231
	v_max_f32_e32 v0, v0, v0
	v_max_f32_e32 v0, v0, v231
	v_sub_f32_e32 v231, v0, v229
	s_mov_b32 s0, 0x42b504f3
	v_cmp_ge_f32_e32 vcc, s0, v231
	v_max_f32_e32 v232, v229, v229
	s_cmp_eq_u64 vcc, exec
	v_max_f32_e32 v232, v232, v0
	s_cselect_b64 vcc, -1, 0
	v_sub_f32_e32 v0, v229, v232
	v_cndmask_b32_e32 v229, v232, v229, vcc
	v_mul_f32_e32 v231, 0xbe0293ee, v229
	v_fmamk_f32 v146, v146, 0x3e0293ee, v231
	v_fmamk_f32 v147, v147, 0x3e0293ee, v231
	v_fmamk_f32 v148, v148, 0x3e0293ee, v231
	v_fmamk_f32 v149, v149, 0x3e0293ee, v231
	v_fmamk_f32 v150, v150, 0x3e0293ee, v231
	v_fmamk_f32 v151, v151, 0x3e0293ee, v231
	v_fmamk_f32 v152, v152, 0x3e0293ee, v231
	v_fmamk_f32 v153, v153, 0x3e0293ee, v231
	v_fmamk_f32 v154, v154, 0x3e0293ee, v231
	v_fmamk_f32 v155, v155, 0x3e0293ee, v231
	v_fmamk_f32 v156, v156, 0x3e0293ee, v231
	v_fmamk_f32 v157, v157, 0x3e0293ee, v231
	v_fmamk_f32 v158, v158, 0x3e0293ee, v231
	v_fmamk_f32 v159, v159, 0x3e0293ee, v231
	v_fmamk_f32 v160, v160, 0x3e0293ee, v231
	v_fmamk_f32 v161, v161, 0x3e0293ee, v231
	v_fmamk_f32 v130, v130, 0x3e0293ee, v231
	v_fmamk_f32 v131, v131, 0x3e0293ee, v231
	v_fmamk_f32 v132, v132, 0x3e0293ee, v231
	v_fmamk_f32 v133, v133, 0x3e0293ee, v231
	v_fmamk_f32 v134, v134, 0x3e0293ee, v231
	v_fmamk_f32 v135, v135, 0x3e0293ee, v231
	v_fmamk_f32 v136, v136, 0x3e0293ee, v231
	v_fmamk_f32 v137, v137, 0x3e0293ee, v231
	v_fmamk_f32 v138, v138, 0x3e0293ee, v231
	v_fmamk_f32 v139, v139, 0x3e0293ee, v231
	v_fmamk_f32 v140, v140, 0x3e0293ee, v231
	v_fmamk_f32 v141, v141, 0x3e0293ee, v231
	v_fmamk_f32 v142, v142, 0x3e0293ee, v231
	v_fmamk_f32 v143, v143, 0x3e0293ee, v231
	v_fmamk_f32 v144, v144, 0x3e0293ee, v231
	v_fmac_f32_e32 v231, 0x3e0293ee, v145
	v_exp_f32_e32 v145, v146
	v_exp_f32_e32 v146, v147
	v_exp_f32_e32 v147, v148
	v_exp_f32_e32 v148, v149
	v_exp_f32_e32 v149, v150
	v_exp_f32_e32 v150, v151
	v_exp_f32_e32 v151, v152
	v_exp_f32_e32 v152, v153
	v_exp_f32_e32 v153, v154
	v_exp_f32_e32 v154, v155
	v_exp_f32_e32 v155, v156
	v_exp_f32_e32 v156, v157
	v_exp_f32_e32 v157, v158
	v_exp_f32_e32 v158, v159
	v_exp_f32_e32 v159, v160
	v_exp_f32_e32 v160, v161
	v_exp_f32_e32 v161, v134
	v_add_f32_e32 v134, 0, v145
	v_add_f32_e32 v134, v146, v134
	v_add_f32_e32 v134, v147, v134
	v_add_f32_e32 v134, v148, v134
	v_add_f32_e32 v134, v149, v134
	v_add_f32_e32 v134, v150, v134
	v_add_f32_e32 v134, v151, v134
	v_add_f32_e32 v134, v152, v134
	v_add_f32_e32 v134, v153, v134
	v_add_f32_e32 v134, v154, v134
	v_add_f32_e32 v134, v155, v134
	v_add_f32_e32 v134, v156, v134
	v_exp_f32_e32 v130, v130
	v_add_f32_e32 v134, v157, v134
	v_exp_f32_e32 v131, v131
	v_add_f32_e32 v134, v158, v134
	v_exp_f32_e32 v132, v132
	v_add_f32_e32 v134, v159, v134
	v_exp_f32_e32 v133, v133
; __device__ __forceinline__ void finishSM(f32x16& p0, f32x16& p1, float alpha, float& l_reg, bf16x8& pa0, bf16x8& pa1, bf16x8& pa2, bf16x8& pa3) {
; #pragma unroll
;   for (int r = 0; r < 16; ++r) p1[r] = __builtin_amdgcn_exp2f(p1[r]);
;   float ps = 0;
; #pragma unroll
;   for (int r = 0; r < 16; ++r) ps += p0[r];
; #pragma unroll
;   for (int r = 0; r < 16; ++r) ps += p1[r];
;   { auto rr = __builtin_amdgcn_permlane32_swap(__float_as_uint(ps), __float_as_uint(ps), false, false);
;     ps = __uint_as_float(rr[0]) + __uint_as_float(rr[1]); }
;   l_reg = l_reg * alpha + ps;
;     ...
;   PK4(p0, 0, pa0); PK4(p0, 8, pa1); PK4(p1, 0, pa2); PK4(p1, 8, pa3);
	v_add_f32_e32 v134, v160, v134
	v_add_f32_e32 v134, v130, v134
	v_exp_f32_e32 v233, v135
	v_add_f32_e32 v134, v131, v134
	v_exp_f32_e32 v234, v136
	v_add_f32_e32 v134, v132, v134
	v_exp_f32_e32 v235, v137
	v_add_f32_e32 v134, v133, v134
	v_exp_f32_e32 v138, v138
	v_add_f32_e32 v134, v161, v134
	v_exp_f32_e32 v139, v139
	v_add_f32_e32 v134, v233, v134
	v_exp_f32_e32 v140, v140
	v_add_f32_e32 v134, v234, v134
	v_exp_f32_e32 v141, v141
	v_add_f32_e32 v134, v235, v134
	v_exp_f32_e32 v236, v142
	v_add_f32_e32 v134, v138, v134
	v_exp_f32_e32 v237, v143
	v_add_f32_e32 v134, v139, v134
	v_exp_f32_e32 v238, v144
	v_add_f32_e32 v134, v140, v134
	v_mul_f32_e32 v0, 0x3e0293ee, v0
	v_exp_f32_e32 v239, v231
	v_add_f32_e32 v134, v141, v134
	v_exp_f32_e32 v0, v0
	v_add_f32_e32 v134, v236, v134
	v_add_f32_e32 v134, v237, v134
	v_add_f32_e32 v134, v238, v134
	v_add_f32_e32 v231, v239, v134
	v_cndmask_b32_e64 v0, v0, 1.0, vcc
	v_mov_b32_e32 v232, v231
	v_cvt_pk_bf16_f32 v134, v145, v146
	v_cvt_pk_bf16_f32 v135, v147, v148
	v_cvt_pk_bf16_f32 v136, v149, v150
	v_cvt_pk_bf16_f32 v137, v151, v152
	v_cvt_pk_bf16_f32 v142, v153, v154
	v_cvt_pk_bf16_f32 v143, v155, v156
	v_cvt_pk_bf16_f32 v144, v157, v158
	v_cvt_pk_bf16_f32 v145, v159, v160
	v_cvt_pk_bf16_f32 v130, v130, v131
	v_cvt_pk_bf16_f32 v131, v132, v133
	v_cvt_pk_bf16_f32 v132, v161, v233
	v_cvt_pk_bf16_f32 v133, v234, v235
	v_cvt_pk_bf16_f32 v138, v138, v139
	v_cvt_pk_bf16_f32 v139, v140, v141
	v_cvt_pk_bf16_f32 v140, v236, v237
	v_cvt_pk_bf16_f32 v141, v238, v239
	v_permlane32_swap_b32_e32 v231, v232
	v_permlane32_swap_b32_e32 v134, v136
	v_permlane32_swap_b32_e32 v135, v137
	v_permlane32_swap_b32_e32 v142, v144
	v_permlane32_swap_b32_e32 v143, v145
	v_permlane32_swap_b32_e32 v130, v132
	v_permlane32_swap_b32_e32 v131, v133
	v_permlane32_swap_b32_e32 v138, v140
	v_permlane32_swap_b32_e32 v139, v141
	v_cmp_gt_f32_e32 vcc, 1.0, v0
	s_cbranch_vccz .Lpl_649
	s_and_saveexec_b64 s[0:1], s[6:7]
	ds_write_b32 v228, v0 offset:128
	s_or_b64 exec, exec, s[0:1]
	s_waitcnt lgkmcnt(0)
	v_add_u32_e32 v146, s67, v223
	ds_read_b128 v[158:161], v146 offset:224
	ds_read_b128 v[154:157], v146 offset:192
	ds_read_b128 v[150:153], v146 offset:160
	ds_read_b128 v[146:149], v146 offset:128
	s_waitcnt lgkmcnt(0)
	v_pk_mul_f32 v[126:127], v[126:127], v[158:159]
	v_pk_mul_f32 v[122:123], v[122:123], v[154:155]
	v_pk_mul_f32 v[118:119], v[118:119], v[150:151]
	v_pk_mul_f32 v[128:129], v[128:129], v[160:161]
	v_pk_mul_f32 v[124:125], v[124:125], v[156:157]
	v_pk_mul_f32 v[120:121], v[120:121], v[152:153]
	v_pk_mul_f32 v[116:117], v[116:117], v[148:149]
	v_pk_mul_f32 v[114:115], v[114:115], v[146:147]
	v_pk_mul_f32 v[110:111], v[110:111], v[158:159]
	v_pk_mul_f32 v[106:107], v[106:107], v[154:155]
	v_pk_mul_f32 v[102:103], v[102:103], v[150:151]
	v_pk_mul_f32 v[112:113], v[112:113], v[160:161]
	v_pk_mul_f32 v[108:109], v[108:109], v[156:157]
	v_pk_mul_f32 v[104:105], v[104:105], v[152:153]
	v_pk_mul_f32 v[100:101], v[100:101], v[148:149]
	v_pk_mul_f32 v[98:99], v[98:99], v[146:147]
	v_pk_mul_f32 v[94:95], v[94:95], v[158:159]
	v_pk_mul_f32 v[90:91], v[90:91], v[154:155]
	v_pk_mul_f32 v[86:87], v[86:87], v[150:151]
	v_pk_mul_f32 v[96:97], v[96:97], v[160:161]
	v_pk_mul_f32 v[92:93], v[92:93], v[156:157]
	v_pk_mul_f32 v[88:89], v[88:89], v[152:153]
	v_pk_mul_f32 v[84:85], v[84:85], v[148:149]
	v_pk_mul_f32 v[82:83], v[82:83], v[146:147]
	v_pk_mul_f32 v[78:79], v[78:79], v[158:159]
	v_pk_mul_f32 v[74:75], v[74:75], v[154:155]
	v_pk_mul_f32 v[70:71], v[70:71], v[150:151]
	v_pk_mul_f32 v[80:81], v[80:81], v[160:161]
	v_pk_mul_f32 v[76:77], v[76:77], v[156:157]
	v_pk_mul_f32 v[72:73], v[72:73], v[152:153]
	v_pk_mul_f32 v[68:69], v[68:69], v[148:149]
	v_pk_mul_f32 v[66:67], v[66:67], v[146:147]
	v_pk_mul_f32 v[62:63], v[62:63], v[158:159]
	v_pk_mul_f32 v[58:59], v[58:59], v[154:155]
	v_pk_mul_f32 v[54:55], v[54:55], v[150:151]
	v_pk_mul_f32 v[64:65], v[64:65], v[160:161]
	v_pk_mul_f32 v[60:61], v[60:61], v[156:157]
	v_pk_mul_f32 v[56:57], v[56:57], v[152:153]
	v_pk_mul_f32 v[52:53], v[52:53], v[148:149]
	v_pk_mul_f32 v[50:51], v[50:51], v[146:147]
	v_pk_mul_f32 v[46:47], v[46:47], v[158:159]
	v_pk_mul_f32 v[42:43], v[42:43], v[154:155]
	v_pk_mul_f32 v[38:39], v[38:39], v[150:151]
	v_pk_mul_f32 v[48:49], v[48:49], v[160:161]
	v_pk_mul_f32 v[44:45], v[44:45], v[156:157]
	v_pk_mul_f32 v[40:41], v[40:41], v[152:153]
	v_pk_mul_f32 v[36:37], v[36:37], v[148:149]
	v_pk_mul_f32 v[34:35], v[34:35], v[146:147]
	v_pk_mul_f32 v[30:31], v[30:31], v[158:159]
	v_pk_mul_f32 v[26:27], v[26:27], v[154:155]
	v_pk_mul_f32 v[22:23], v[22:23], v[150:151]
	v_pk_mul_f32 v[32:33], v[32:33], v[160:161]
	v_pk_mul_f32 v[28:29], v[28:29], v[156:157]
	v_pk_mul_f32 v[24:25], v[24:25], v[152:153]
	v_pk_mul_f32 v[20:21], v[20:21], v[148:149]
	v_pk_mul_f32 v[18:19], v[18:19], v[146:147]
	v_pk_mul_f32 v[14:15], v[14:15], v[158:159]
	v_pk_mul_f32 v[10:11], v[10:11], v[154:155]
	v_pk_mul_f32 v[6:7], v[6:7], v[150:151]
	v_pk_mul_f32 v[16:17], v[16:17], v[160:161]
	v_pk_mul_f32 v[12:13], v[12:13], v[156:157]
	v_pk_mul_f32 v[8:9], v[8:9], v[152:153]
	v_pk_mul_f32 v[4:5], v[4:5], v[148:149]
	v_pk_mul_f32 v[2:3], v[2:3], v[146:147]
; #define SBAR() __builtin_amdgcn_sched_barrier(0)
; template <int D0> __device__ __forceinline__ void pv_one(f32x16& od, int vb, bf16x8 pa0, bf16x8 pa1, bf16x8 pa2, bf16x8 pa3) {
;   const s16x4 l0 = tr_read<v_rd_off(D0, 0, 0)>(vb), h0 = tr_read<v_rd_off(D0, 0, 1)>(vb), l1 = tr_read<v_rd_off(D0, 1, 0)>(vb), h1 = tr_read<v_rd_off(D0, 1, 1)>(vb);
;   const s16x4 l2 = tr_read<v_rd_off(D0, 2, 0)>(vb), h2 = tr_read<v_rd_off(D0, 2, 1)>(vb), l3 = tr_read<v_rd_off(D0, 3, 0)>(vb), h3 = tr_read<v_rd_off(D0, 3, 1)>(vb);
;   asm volatile("s_waitcnt lgkmcnt(0)" ::: "memory"); SBAR();
;     ...
;   od = __builtin_amdgcn_mfma_f32_32x32x16_bf16(pa0, PK(l0, h0), od, 0, 0, 0);
;   od = __builtin_amdgcn_mfma_f32_32x32x16_bf16(pa1, PK(l1, h1), od, 0, 0, 0);
;   od = __builtin_amdgcn_mfma_f32_32x32x16_bf16(pa2, PK(l2, h2), od, 0, 0, 0);
;   od = __builtin_amdgcn_mfma_f32_32x32x16_bf16(pa3, PK(l3, h3), od, 0, 0, 0);
;     ...
; }
; __device__ __forceinline__ void pv_d0(f32x16* o, int vb, bf16x8 pa0, bf16x8 pa1, bf16x8 pa2, bf16x8 pa3) {
;   pv_one<0>(o[0], vb, pa0, pa1, pa2, pa3); pv_one<1>(o[1], vb, pa0, pa1, pa2, pa3); pv_one<2>(o[2], vb, pa0, pa1, pa2, pa3); pv_one<3>(o[3], vb, pa0, pa1, pa2, pa3);
; }
; template <int LDO>
; __device__ __forceinline__ void attn_unit_dv(const bf16_t* __restrict__ Qb, const bf16_t* __restrict__ Kh, const bf16_t* __restrict__ Vh, bf16_t* __restrict__ Ob, int NT, char* lds, LAS3 unsigned char* ldsl) {
;     ...
;   if (wid >= 4) __builtin_amdgcn_s_setprio(1);
;   DMA_KV(0, 0);
;   const bf16_t* Qw = Qb + (long)(wid * QBLK + r32) * LDQ + hi * 8;
; #pragma unroll
;   for (int d0 = 0; d0 < 8; ++d0) qr[d0] = ld8(Qw + d0 * 16);
;   const int vb0 = (int)(uintptr_t)(lds + DV_V0) + v_rd_base(lane);
;   asm volatile("s_waitcnt vmcnt(0) lgkmcnt(0)" ::: "memory"); __builtin_amdgcn_s_barrier(); asm volatile("" ::: "memory");
;   for (int t = 0; t < NT; ++t) {
;     const int buf = t & 1;
;     f32x16 p0, p1; float mn, alpha; bf16x8 pa0, pa1, pa2, pa3;
;     qkt<false>(p0, p1, (const bf16_t*)(lds + DV_K0 + buf * 16384), qr, r32, hi, 0);
;     SBAR();
;     if (t + 1 < NT) DMA_KV(t + 1, buf ^ 1);
;     SBAR();
;     partialSM<false>(p0, p1, m_reg, mn, alpha);
;     finishSM(p0, p1, alpha, l_reg, pa0, pa1, pa2, pa3);
;     RESC8(alpha);
;     SBAR();
;     pv_d0(o, vb0 + buf * 32768, pa0, pa1, pa2, pa3);
;     pv_d0(o + 4, vb0 + buf * 32768 + 16384, pa0, pa1, pa2, pa3);
.Lpl_649:
	s_waitcnt vmcnt(4)
	s_barrier
	s_lshl_b32 s0, s69, 14
	s_add_i32 s0, s35, s0
	v_lshl_add_u64 v[254:255], s[22:23], 0, v[206:207]
	v_lshl_add_u64 v[254:255], v[254:255], 0, s[64:65]
	s_mov_b32 m0, s0
	s_nop 0
	global_load_lds_dwordx4 v[254:255], off
	v_lshl_add_u64 v[254:255], s[22:23], 0, v[204:205]
	v_lshl_add_u64 v[254:255], v[254:255], 0, s[64:65]
	s_add_i32 m0, s0, 0x400
	s_nop 0
	global_load_lds_dwordx4 v[254:255], off
	s_lshl_b32 s0, s101, 15
	s_add_i32 s33, s66, s0
	v_lshl_add_u64 v[254:255], s[22:23], 0, v[202:203]
	s_mov_b64 s[0:1], 0x33e10000
	v_lshl_add_u64 v[254:255], v[254:255], 0, s[0:1]
	s_add_i32 m0, s33, 0x8000
	s_mov_b64 s[0:1], 0x80
	global_load_lds_dwordx4 v[254:255], off
	v_lshl_add_u64 v[254:255], v[254:255], 0, s[0:1]
	s_add_i32 m0, s33, 0x8400
	s_mov_b64 s[0:1], 0x780
	global_load_lds_dwordx4 v[254:255], off
	v_lshl_add_u64 v[254:255], v[254:255], 0, s[0:1]
	s_add_i32 m0, s33, 0x8800
	s_mov_b64 s[0:1], 0x80
	global_load_lds_dwordx4 v[254:255], off
	v_lshl_add_u64 v[254:255], v[254:255], 0, s[0:1]
	s_add_i32 m0, s33, 0x8c00
	s_nop 0
	global_load_lds_dwordx4 v[254:255], off
	v_add_f32_e32 v146, v231, v232
	v_fmac_f32_e32 v146, v230, v0
	s_add_i32 s68, s68, 1
	v_lshl_add_u32 v0, s98, 15, v224
	ds_read_b64_tr_b16 v[148:149], v0 offset:0
	ds_read_b64_tr_b16 v[150:151], v0 offset:0x800
	ds_read_b64_tr_b16 v[152:153], v0 offset:0x1000
	ds_read_b64_tr_b16 v[154:155], v0 offset:0x1800
	ds_read_b64_tr_b16 v[156:157], v0 offset:0x2000
	ds_read_b64_tr_b16 v[158:159], v0 offset:0x2800
	ds_read_b64_tr_b16 v[230:231], v0 offset:0x3000
	ds_read_b64_tr_b16 v[232:233], v0 offset:0x3800
	s_waitcnt lgkmcnt(0)
	s_nop 0
	v_mfma_f32_32x32x16_bf16 v[114:129], v[134:137], v[148:151], v[114:129]
	ds_read_b64_tr_b16 v[148:149], v0 offset:0x200
	ds_read_b64_tr_b16 v[150:151], v0 offset:0xa00
	v_mfma_f32_32x32x16_bf16 v[114:129], v[142:145], v[152:155], v[114:129]
	ds_read_b64_tr_b16 v[152:153], v0 offset:0x1200
	ds_read_b64_tr_b16 v[154:155], v0 offset:0x1a00
	v_mfma_f32_32x32x16_bf16 v[114:129], v[130:133], v[156:159], v[114:129]
	ds_read_b64_tr_b16 v[156:157], v0 offset:0x2200
	ds_read_b64_tr_b16 v[158:159], v0 offset:0x2a00
	ds_read_b64_tr_b16 v[234:235], v0 offset:0x3200
	ds_read_b64_tr_b16 v[236:237], v0 offset:0x3a00
	s_waitcnt lgkmcnt(0)
	v_mfma_f32_32x32x16_bf16 v[114:129], v[138:141], v[230:233], v[114:129]
	v_mfma_f32_32x32x16_bf16 v[98:113], v[134:137], v[148:151], v[98:113]
	ds_read_b64_tr_b16 v[148:149], v0 offset:0x400
	ds_read_b64_tr_b16 v[150:151], v0 offset:0xc00
	v_mfma_f32_32x32x16_bf16 v[98:113], v[142:145], v[152:155], v[98:113]
	ds_read_b64_tr_b16 v[152:153], v0 offset:0x1400
	ds_read_b64_tr_b16 v[154:155], v0 offset:0x1c00
	v_mfma_f32_32x32x16_bf16 v[98:113], v[130:133], v[156:159], v[98:113]
	ds_read_b64_tr_b16 v[156:157], v0 offset:0x2400
	ds_read_b64_tr_b16 v[158:159], v0 offset:0x2c00
	ds_read_b64_tr_b16 v[230:231], v0 offset:0x3400
	ds_read_b64_tr_b16 v[232:233], v0 offset:0x3c00
	s_waitcnt lgkmcnt(0)
	v_mfma_f32_32x32x16_bf16 v[98:113], v[138:141], v[234:237], v[98:113]
	v_mfma_f32_32x32x16_bf16 v[82:97], v[134:137], v[148:151], v[82:97]
	ds_read_b64_tr_b16 v[148:149], v0 offset:0x600
	ds_read_b64_tr_b16 v[150:151], v0 offset:0xe00
	v_mfma_f32_32x32x16_bf16 v[82:97], v[142:145], v[152:155], v[82:97]
	ds_read_b64_tr_b16 v[152:153], v0 offset:0x1600
	ds_read_b64_tr_b16 v[154:155], v0 offset:0x1e00
	v_mfma_f32_32x32x16_bf16 v[82:97], v[130:133], v[156:159], v[82:97]
	ds_read_b64_tr_b16 v[156:157], v0 offset:0x2600
	ds_read_b64_tr_b16 v[158:159], v0 offset:0x2e00
	ds_read_b64_tr_b16 v[234:235], v0 offset:0x3600
	ds_read_b64_tr_b16 v[236:237], v0 offset:0x3e00
	s_waitcnt lgkmcnt(0)
	v_mfma_f32_32x32x16_bf16 v[82:97], v[138:141], v[230:233], v[82:97]
	v_mfma_f32_32x32x16_bf16 v[66:81], v[134:137], v[148:151], v[66:81]
	v_add_u32_e32 v0, 0x4000, v0
	ds_read_b64_tr_b16 v[148:149], v0 offset:0
	ds_read_b64_tr_b16 v[150:151], v0 offset:0x800
	v_mfma_f32_32x32x16_bf16 v[66:81], v[142:145], v[152:155], v[66:81]
	ds_read_b64_tr_b16 v[152:153], v0 offset:0x1000
	ds_read_b64_tr_b16 v[154:155], v0 offset:0x1800
	v_mfma_f32_32x32x16_bf16 v[66:81], v[130:133], v[156:159], v[66:81]
	ds_read_b64_tr_b16 v[156:157], v0 offset:0x2000
	ds_read_b64_tr_b16 v[158:159], v0 offset:0x2800
	ds_read_b64_tr_b16 v[230:231], v0 offset:0x3000
	ds_read_b64_tr_b16 v[232:233], v0 offset:0x3800
	s_waitcnt lgkmcnt(0)
	v_mfma_f32_32x32x16_bf16 v[66:81], v[138:141], v[234:237], v[66:81]
	v_mfma_f32_32x32x16_bf16 v[50:65], v[134:137], v[148:151], v[50:65]
	ds_read_b64_tr_b16 v[148:149], v0 offset:0x200
	ds_read_b64_tr_b16 v[150:151], v0 offset:0xa00
	v_mfma_f32_32x32x16_bf16 v[50:65], v[142:145], v[152:155], v[50:65]
	ds_read_b64_tr_b16 v[152:153], v0 offset:0x1200
	ds_read_b64_tr_b16 v[154:155], v0 offset:0x1a00
	v_mfma_f32_32x32x16_bf16 v[50:65], v[130:133], v[156:159], v[50:65]
	ds_read_b64_tr_b16 v[156:157], v0 offset:0x2200
	ds_read_b64_tr_b16 v[158:159], v0 offset:0x2a00
	ds_read_b64_tr_b16 v[234:235], v0 offset:0x3200
	ds_read_b64_tr_b16 v[236:237], v0 offset:0x3a00
	s_waitcnt lgkmcnt(0)
	v_mfma_f32_32x32x16_bf16 v[50:65], v[138:141], v[230:233], v[50:65]
	v_mfma_f32_32x32x16_bf16 v[34:49], v[134:137], v[148:151], v[34:49]
	ds_read_b64_tr_b16 v[148:149], v0 offset:0x400
	ds_read_b64_tr_b16 v[150:151], v0 offset:0xc00
	v_mfma_f32_32x32x16_bf16 v[34:49], v[142:145], v[152:155], v[34:49]
	ds_read_b64_tr_b16 v[152:153], v0 offset:0x1400
	ds_read_b64_tr_b16 v[154:155], v0 offset:0x1c00
	v_mfma_f32_32x32x16_bf16 v[34:49], v[130:133], v[156:159], v[34:49]
	ds_read_b64_tr_b16 v[156:157], v0 offset:0x2400
	ds_read_b64_tr_b16 v[158:159], v0 offset:0x2c00
	ds_read_b64_tr_b16 v[230:231], v0 offset:0x3400
	ds_read_b64_tr_b16 v[232:233], v0 offset:0x3c00
	s_waitcnt lgkmcnt(0)
	v_mfma_f32_32x32x16_bf16 v[34:49], v[138:141], v[234:237], v[34:49]
	v_mfma_f32_32x32x16_bf16 v[18:33], v[134:137], v[148:151], v[18:33]
	ds_read_b64_tr_b16 v[148:149], v0 offset:0x600
	ds_read_b64_tr_b16 v[150:151], v0 offset:0xe00
	v_mfma_f32_32x32x16_bf16 v[18:33], v[142:145], v[152:155], v[18:33]
	ds_read_b64_tr_b16 v[152:153], v0 offset:0x1600
	ds_read_b64_tr_b16 v[154:155], v0 offset:0x1e00
	v_mfma_f32_32x32x16_bf16 v[18:33], v[130:133], v[156:159], v[18:33]
	ds_read_b64_tr_b16 v[156:157], v0 offset:0x2600
	ds_read_b64_tr_b16 v[158:159], v0 offset:0x2e00
	ds_read_b64_tr_b16 v[234:235], v0 offset:0x3600
	ds_read_b64_tr_b16 v[236:237], v0 offset:0x3e00
	s_waitcnt lgkmcnt(0)
	v_mfma_f32_32x32x16_bf16 v[18:33], v[138:141], v[230:233], v[18:33]
	v_mfma_f32_32x32x16_bf16 v[2:17], v[134:137], v[148:151], v[2:17]
	s_waitcnt vmcnt(6) lgkmcnt(0)
	s_barrier
; template <int LDO>
; __device__ __forceinline__ void attn_unit_dv(const bf16_t* __restrict__ Qb, const bf16_t* __restrict__ Kh, const bf16_t* __restrict__ Vh, bf16_t* __restrict__ Ob, int NT, char* lds, LAS3 unsigned char* ldsl) {
;     ...
;     pv_d0(o, vb0 + buf * 32768, pa0, pa1, pa2, pa3);
;     pv_d0(o + 4, vb0 + buf * 32768 + 16384, pa0, pa1, pa2, pa3);
;     asm volatile("s_waitcnt vmcnt(0) lgkmcnt(0)" ::: "memory"); __builtin_amdgcn_s_barrier(); asm volatile("" ::: "memory");
;   }
;   __builtin_amdgcn_s_setprio(0);
;   if (hi == 0) li_l[r32] = l_reg; asm volatile("s_waitcnt lgkmcnt(0)" ::: "memory");
	s_mov_b32 s98, s100
	s_mov_b32 s100, s101
	s_add_i32 s101, s101, 1
	s_cmp_eq_u32 s101, 3
	s_cselect_b32 s101, 0, s101
	s_mov_b64 s[0:1], 0x8000
	v_lshl_add_u64 v[202:203], v[202:203], 0, s[0:1]
	v_lshl_add_u64 v[204:205], v[204:205], 0, s[64:65]
	v_lshl_add_u64 v[206:207], v[206:207], 0, s[64:65]
	v_mfma_f32_32x32x16_bf16 v[2:17], v[142:145], v[152:155], v[2:17]
	s_cmpk_eq_i32 s68, 0x100
	v_mfma_f32_32x32x16_bf16 v[2:17], v[130:133], v[156:159], v[2:17]
	v_mfma_f32_32x32x16_bf16 v[2:17], v[138:141], v[234:237], v[2:17]
	s_cbranch_scc1 .LBB0_651
	v_mov_b32_e32 v230, v146
	s_branch .Lpl_top
.LBB0_651:
	s_setprio 0
	s_cmpk_ge_u32 s99, 0x100
	s_cbranch_scc1 .Lpl_skip_y
	s_barrier
.Lpl_skip_y:
	s_waitcnt vmcnt(0)
	s_barrier
	s_and_saveexec_b64 s[0:1], s[6:7]
	s_cbranch_execz .LBB0_639
	ds_write_b32 v228, v146
	s_branch .LBB0_639

; __global__ void __launch_bounds__(NWAVES * 64, 2) mk_fwd(Args args) {
	.amdhsa_kernel _Z6mk_fwd4Args
		.amdhsa_group_segment_fixed_size 0
		.amdhsa_private_segment_fixed_size 0
		.amdhsa_kernarg_size 472
		.amdhsa_user_sgpr_count 2
		.amdhsa_user_sgpr_dispatch_ptr 0
		.amdhsa_user_sgpr_queue_ptr 0
		.amdhsa_user_sgpr_kernarg_segment_ptr 1
		.amdhsa_user_sgpr_dispatch_id 0
		.amdhsa_user_sgpr_kernarg_preload_length 0
		.amdhsa_user_sgpr_kernarg_preload_offset 0
		.amdhsa_user_sgpr_private_segment_size 0
		.amdhsa_uses_dynamic_stack 0
		.amdhsa_enable_private_segment 0
		.amdhsa_system_sgpr_workgroup_id_x 1
		.amdhsa_system_sgpr_workgroup_id_y 0
		.amdhsa_system_sgpr_workgroup_id_z 0
		.amdhsa_system_sgpr_workgroup_info 0
		.amdhsa_system_vgpr_workitem_id 2
		.amdhsa_next_free_vgpr 256
		.amdhsa_next_free_sgpr 102
		.amdhsa_accum_offset 256
		.amdhsa_reserve_vcc 1
		.amdhsa_float_round_mode_32 0
		.amdhsa_float_round_mode_16_64 0
		.amdhsa_float_denorm_mode_32 3
		.amdhsa_float_denorm_mode_16_64 3
		.amdhsa_dx10_clamp 1
		.amdhsa_ieee_mode 1
		.amdhsa_fp16_overflow 0
		.amdhsa_tg_split 0
		.amdhsa_exception_fp_ieee_invalid_op 0
		.amdhsa_exception_fp_denorm_src 0
		.amdhsa_exception_fp_ieee_div_zero 0
		.amdhsa_exception_fp_ieee_overflow 0
		.amdhsa_exception_fp_ieee_underflow 0
		.amdhsa_exception_fp_ieee_inexact 0
		.amdhsa_exception_int_div_zero 0
	.end_amdhsa_kernel

; __global__ void __launch_bounds__(NWAVES * 64, 2) mk_fwd(Args args) {
.Lfunc_end0:
	.size	_Z6mk_fwd4Args, .Lfunc_end0-_Z6mk_fwd4Args
	.set _Z6mk_fwd4Args.num_vgpr, 256
	.set _Z6mk_fwd4Args.num_agpr, 0
	.set _Z6mk_fwd4Args.numbered_sgpr, 102
	.set _Z6mk_fwd4Args.num_named_barrier, 0
	.set _Z6mk_fwd4Args.private_seg_size, 0
	.set _Z6mk_fwd4Args.uses_vcc, 1
	.set _Z6mk_fwd4Args.uses_flat_scratch, 0
	.set _Z6mk_fwd4Args.has_dyn_sized_stack, 0
	.set _Z6mk_fwd4Args.has_recursion, 0
	.set _Z6mk_fwd4Args.has_indirect_call, 0

; __global__ void __launch_bounds__(NWAVES * 64, 2) mk_fwd(Args args) {
amdhsa.kernels:
  - .agpr_count:     0
    .args:
      - .offset:         0
        .size:           216
        .value_kind:     by_value
      - .offset:         216
        .size:           4
        .value_kind:     hidden_block_count_x
      - .offset:         220
        .size:           4
        .value_kind:     hidden_block_count_y
      - .offset:         224
        .size:           4
        .value_kind:     hidden_block_count_z
      - .offset:         228
        .size:           2
        .value_kind:     hidden_group_size_x
      - .offset:         230
        .size:           2
        .value_kind:     hidden_group_size_y
      - .offset:         232
        .size:           2
        .value_kind:     hidden_group_size_z
      - .offset:         234
        .size:           2
        .value_kind:     hidden_remainder_x
      - .offset:         236
        .size:           2
        .value_kind:     hidden_remainder_y
      - .offset:         238
        .size:           2
        .value_kind:     hidden_remainder_z
      - .offset:         256
        .size:           8
        .value_kind:     hidden_global_offset_x
      - .offset:         264
        .size:           8
        .value_kind:     hidden_global_offset_y
      - .offset:         272
        .size:           8
        .value_kind:     hidden_global_offset_z
      - .offset:         280
        .size:           2
        .value_kind:     hidden_grid_dims
      - .offset:         304
        .size:           8
        .value_kind:     hidden_multigrid_sync_arg
      - .offset:         336
        .size:           4
        .value_kind:     hidden_dynamic_lds_size
    .group_segment_fixed_size: 0
    .kernarg_segment_align: 8
    .kernarg_segment_size: 472
    .language:       OpenCL C
    .language_version:
      - 2
      - 0
    .max_flat_workgroup_size: 512
    .name:           _Z6mk_fwd4Args
    .private_segment_fixed_size: 0
    .sgpr_count:     108
    .sgpr_spill_count: 48
    .symbol:         _Z6mk_fwd4Args.kd
    .uniform_work_group_size: 1
    .uses_dynamic_stack: false
    .vgpr_count:     256
    .vgpr_spill_count: 0
    .wavefront_size: 64
